# rope (in-proj layer 1) epilogue per-head sum-of-squares reductions via v_permlane16/32_swap instead of ds_bpermute (16 more sites); on top of v27
# speedup vs baseline: 1.0137x; 1.0021x over previous
;     __device__ __forceinline__ void operator()(f32x4 (&acc)[2][2][4][2], const Unit& u, int wr, int wc, int fr_in, int fq_in) const {
;     ...
;         if (u.pn < 5) {
; #pragma unroll
;             for (int ai = 0; ai < 2; ++ai)
; #pragma unroll
;                 for (int m = 0; m < 4; ++m) { float s = 0.f;
; #pragma unroll
;                     for (int bj = 0; bj < 2; ++bj)
; #pragma unroll
;                         for (int n = 0; n < 2; ++n) { const f32x4 v = acc[ai][bj][m][n]; s += (v[0] * v[0] + v[1] * v[1]) + (v[2] * v[2] + v[3] * v[3]); }
;                     s += __shfl_xor(s, 16); s += __shfl_xor(s, 32);
;                     if (fq == 0) PS[(lr0 + ai * HALF + m * 16) * 4 + wc] = s; }
.LBB0_1346:
	s_andn2_b64 vcc, exec, s[4:5]
	v_readlane_b32 s68, v254, 30
	s_cbranch_vccnz .LBB0_1364
	v_mul_f32_e32 v2, v163, v163
	v_mul_f32_e32 v3, v161, v161
	v_fmac_f32_e32 v2, v162, v162
	v_fmac_f32_e32 v3, v160, v160
	v_add_f32_e32 v2, v2, v3
	v_mul_f32_e32 v3, v165, v165
	v_mul_f32_e32 v4, v159, v159
	v_fmac_f32_e32 v3, v164, v164
	v_fmac_f32_e32 v4, v158, v158
	v_add_f32_e32 v3, v3, v4
	v_add_f32_e32 v2, v2, v3
	v_mul_f32_e32 v3, v157, v157
	v_mul_f32_e32 v4, v155, v155
	v_fmac_f32_e32 v3, v156, v156
	v_fmac_f32_e32 v4, v154, v154
	v_and_b32_e32 v1, 64, v173
	v_add_f32_e32 v3, v3, v4
	v_xor_b32_e32 v0, 16, v173
	v_add_u32_e32 v1, 64, v1
	v_add_f32_e32 v2, v3, v2
	v_mul_f32_e32 v3, v151, v151
	v_mul_f32_e32 v4, v127, v127
	v_cmp_lt_i32_e32 vcc, v0, v1
	v_fmac_f32_e32 v3, v150, v150
	v_fmac_f32_e32 v4, v126, v126
	v_cndmask_b32_e32 v0, v173, v0, vcc
	v_add_f32_e32 v3, v3, v4
	v_lshlrev_b32_e32 v0, 2, v0
	v_add_f32_e32 v2, v3, v2
	v_mov_b32_e32 v3, v2
	s_nop 1
	v_permlane16_swap_b32_e32 v3, v2
	v_xor_b32_e32 v4, 32, v173
	v_cmp_lt_i32_e32 vcc, v4, v1
	s_nop 1
	v_cndmask_b32_e32 v1, v173, v4, vcc
	v_lshlrev_b32_e32 v1, 2, v1
	s_waitcnt lgkmcnt(0)
	v_add_f32_e32 v4, v2, v3
	v_mov_b32_e32 v5, v4
	s_nop 1
	v_permlane32_swap_b32_e32 v5, v4
	v_lshlrev_b32_e32 v2, 4, v178
	v_cmp_gt_u32_e32 vcc, 16, v179
	v_add_u32_e32 v3, s53, v2
	s_and_saveexec_b64 s[4:5], vcc
	s_cbranch_execz .LBB0_1349
	s_waitcnt lgkmcnt(0)
	v_add_f32_e32 v4, v4, v5
	ds_write_b32 v3, v4
.LBB0_1349:
	s_or_b64 exec, exec, s[4:5]
	v_mul_f32_e32 v4, v153, v153
	s_waitcnt lgkmcnt(0)
	v_mul_f32_e32 v5, v125, v125
	v_fmac_f32_e32 v4, v152, v152
	v_fmac_f32_e32 v5, v124, v124
	v_add_f32_e32 v4, v4, v5
	v_mul_f32_e32 v5, v123, v123
	v_mul_f32_e32 v6, v121, v121
	v_fmac_f32_e32 v5, v122, v122
	v_fmac_f32_e32 v6, v120, v120
	v_add_f32_e32 v5, v5, v6
	v_add_f32_e32 v4, v4, v5
	v_mul_f32_e32 v5, v119, v119
	v_mul_f32_e32 v6, v117, v117
	v_fmac_f32_e32 v5, v118, v118
	v_fmac_f32_e32 v6, v116, v116
	v_add_f32_e32 v5, v5, v6
	v_add_f32_e32 v4, v5, v4
	v_mul_f32_e32 v5, v115, v115
	v_mul_f32_e32 v6, v113, v113
	v_fmac_f32_e32 v5, v114, v114
	v_fmac_f32_e32 v6, v112, v112
	v_add_f32_e32 v5, v5, v6
	v_add_f32_e32 v4, v5, v4
	v_mov_b32_e32 v5, v4
	s_nop 1
	v_permlane16_swap_b32_e32 v5, v4
	s_waitcnt lgkmcnt(0)
	v_add_f32_e32 v4, v4, v5
	v_mov_b32_e32 v5, v4
	s_nop 1
	v_permlane32_swap_b32_e32 v5, v4
	s_and_saveexec_b64 s[4:5], vcc
	s_cbranch_execz .LBB0_1351
	s_waitcnt lgkmcnt(0)
	v_add_f32_e32 v4, v4, v5
	ds_write_b32 v3, v4 offset:256
.LBB0_1351:
	s_or_b64 exec, exec, s[4:5]
	v_mul_f32_e32 v4, v111, v111
	s_waitcnt lgkmcnt(0)
	v_mul_f32_e32 v5, v109, v109
	v_fmac_f32_e32 v4, v110, v110
	v_fmac_f32_e32 v5, v108, v108
	v_add_f32_e32 v4, v4, v5
	v_mul_f32_e32 v5, v107, v107
	v_mul_f32_e32 v6, v105, v105
	v_fmac_f32_e32 v5, v106, v106
	v_fmac_f32_e32 v6, v104, v104
	v_add_f32_e32 v5, v5, v6
	v_add_f32_e32 v4, v4, v5
	v_mul_f32_e32 v5, v103, v103
	v_mul_f32_e32 v6, v101, v101
	v_fmac_f32_e32 v5, v102, v102
	v_fmac_f32_e32 v6, v100, v100
	v_add_f32_e32 v5, v5, v6
	v_add_f32_e32 v4, v5, v4
	v_mul_f32_e32 v5, v99, v99
	v_mul_f32_e32 v6, v97, v97
	v_fmac_f32_e32 v5, v98, v98
	v_fmac_f32_e32 v6, v96, v96
	v_add_f32_e32 v5, v5, v6
	v_add_f32_e32 v4, v5, v4
	v_mov_b32_e32 v5, v4
	s_nop 1
	v_permlane16_swap_b32_e32 v5, v4
	s_waitcnt lgkmcnt(0)
	v_add_f32_e32 v4, v4, v5
	v_mov_b32_e32 v5, v4
	s_nop 1
	v_permlane32_swap_b32_e32 v5, v4
	s_and_saveexec_b64 s[4:5], vcc
	s_cbranch_execz .LBB0_1353
	s_waitcnt lgkmcnt(0)
	v_add_f32_e32 v4, v4, v5
	ds_write_b32 v3, v4 offset:512
.LBB0_1353:
	s_or_b64 exec, exec, s[4:5]
	v_mul_f32_e32 v4, v95, v95
	s_waitcnt lgkmcnt(0)
	v_mul_f32_e32 v5, v93, v93
	v_fmac_f32_e32 v4, v94, v94
	v_fmac_f32_e32 v5, v92, v92
	v_add_f32_e32 v4, v4, v5
	v_mul_f32_e32 v5, v91, v91
	v_mul_f32_e32 v6, v89, v89
	v_fmac_f32_e32 v5, v90, v90
	v_fmac_f32_e32 v6, v88, v88
	v_add_f32_e32 v5, v5, v6
	v_add_f32_e32 v4, v4, v5
	v_mul_f32_e32 v5, v87, v87
	v_mul_f32_e32 v6, v85, v85
	v_fmac_f32_e32 v5, v86, v86
	v_fmac_f32_e32 v6, v84, v84
	v_add_f32_e32 v5, v5, v6
	v_add_f32_e32 v4, v5, v4
	v_mul_f32_e32 v5, v83, v83
	v_mul_f32_e32 v6, v81, v81
	v_fmac_f32_e32 v5, v82, v82
	v_fmac_f32_e32 v6, v80, v80
	v_add_f32_e32 v5, v5, v6
	v_add_f32_e32 v4, v5, v4
	v_mov_b32_e32 v5, v4
	s_nop 1
	v_permlane16_swap_b32_e32 v5, v4
	s_waitcnt lgkmcnt(0)
	v_add_f32_e32 v4, v4, v5
	v_mov_b32_e32 v5, v4
	s_nop 1
	v_permlane32_swap_b32_e32 v5, v4
	s_and_saveexec_b64 s[4:5], vcc
	s_cbranch_execz .LBB0_1355
	s_waitcnt lgkmcnt(0)
	v_add_f32_e32 v4, v4, v5
	ds_write_b32 v3, v4 offset:768
;     __device__ __forceinline__ void operator()(f32x4 (&acc)[2][2][4][2], const Unit& u, int wr, int wc, int fr_in, int fq_in) const {
;     ...
;                 for (int m = 0; m < 4; ++m) { float s = 0.f;
; #pragma unroll
;                     for (int bj = 0; bj < 2; ++bj)
; #pragma unroll
;                         for (int n = 0; n < 2; ++n) { const f32x4 v = acc[ai][bj][m][n]; s += (v[0] * v[0] + v[1] * v[1]) + (v[2] * v[2] + v[3] * v[3]); }
;                     s += __shfl_xor(s, 16); s += __shfl_xor(s, 32);
;                     if (fq == 0) PS[(lr0 + ai * HALF + m * 16) * 4 + wc] = s; }
.LBB0_1355:
	s_or_b64 exec, exec, s[4:5]
	v_mul_f32_e32 v3, v79, v79
	v_mul_f32_e32 v4, v77, v77
	v_fmac_f32_e32 v3, v78, v78
	v_fmac_f32_e32 v4, v76, v76
	v_add_f32_e32 v3, v3, v4
	v_mul_f32_e32 v4, v75, v75
	s_waitcnt lgkmcnt(0)
	v_mul_f32_e32 v5, v73, v73
	v_fmac_f32_e32 v4, v74, v74
	v_fmac_f32_e32 v5, v72, v72
	v_add_f32_e32 v4, v4, v5
	v_add_f32_e32 v3, v3, v4
	v_mul_f32_e32 v4, v71, v71
	v_mul_f32_e32 v5, v69, v69
	v_fmac_f32_e32 v4, v70, v70
	v_fmac_f32_e32 v5, v68, v68
	v_add_f32_e32 v4, v4, v5
	v_add_f32_e32 v3, v4, v3
	v_mul_f32_e32 v4, v67, v67
	v_mul_f32_e32 v5, v65, v65
	v_fmac_f32_e32 v4, v66, v66
	v_fmac_f32_e32 v5, v64, v64
	v_add_f32_e32 v4, v4, v5
	v_add_f32_e32 v3, v4, v3
	v_mov_b32_e32 v4, v3
	s_nop 1
	v_permlane16_swap_b32_e32 v4, v3
	v_add_u32_e32 v2, s54, v2
	s_waitcnt lgkmcnt(0)
	v_add_f32_e32 v3, v3, v4
	v_mov_b32_e32 v4, v3
	s_nop 1
	v_permlane32_swap_b32_e32 v4, v3
	s_and_saveexec_b64 s[4:5], vcc
	s_cbranch_execz .LBB0_1357
	s_waitcnt lgkmcnt(0)
	v_add_f32_e32 v3, v3, v4
	ds_write_b32 v2, v3
.LBB0_1357:
	s_or_b64 exec, exec, s[4:5]
	v_mul_f32_e32 v3, v63, v63
	s_waitcnt lgkmcnt(0)
	v_mul_f32_e32 v4, v61, v61
	v_fmac_f32_e32 v3, v62, v62
	v_fmac_f32_e32 v4, v60, v60
	v_add_f32_e32 v3, v3, v4
	v_mul_f32_e32 v4, v59, v59
	v_mul_f32_e32 v5, v57, v57
	v_fmac_f32_e32 v4, v58, v58
	v_fmac_f32_e32 v5, v56, v56
	v_add_f32_e32 v4, v4, v5
	v_add_f32_e32 v3, v3, v4
	v_mul_f32_e32 v4, v55, v55
	v_mul_f32_e32 v5, v53, v53
	v_fmac_f32_e32 v4, v54, v54
	v_fmac_f32_e32 v5, v52, v52
	v_add_f32_e32 v4, v4, v5
	v_add_f32_e32 v3, v4, v3
	v_mul_f32_e32 v4, v51, v51
	v_mul_f32_e32 v5, v49, v49
	v_fmac_f32_e32 v4, v50, v50
	v_fmac_f32_e32 v5, v48, v48
	v_add_f32_e32 v4, v4, v5
	v_add_f32_e32 v3, v4, v3
	v_mov_b32_e32 v4, v3
	s_nop 1
	v_permlane16_swap_b32_e32 v4, v3
	s_waitcnt lgkmcnt(0)
	v_add_f32_e32 v3, v3, v4
	v_mov_b32_e32 v4, v3
	s_nop 1
	v_permlane32_swap_b32_e32 v4, v3
	s_and_saveexec_b64 s[4:5], vcc
	s_cbranch_execz .LBB0_1359
	s_waitcnt lgkmcnt(0)
	v_add_f32_e32 v3, v3, v4
	ds_write_b32 v2, v3 offset:256
.LBB0_1359:
	s_or_b64 exec, exec, s[4:5]
	v_mul_f32_e32 v3, v47, v47
	s_waitcnt lgkmcnt(0)
	v_mul_f32_e32 v4, v45, v45
	v_fmac_f32_e32 v3, v46, v46
	v_fmac_f32_e32 v4, v44, v44
	v_add_f32_e32 v3, v3, v4
	v_mul_f32_e32 v4, v43, v43
	v_mul_f32_e32 v5, v41, v41
	v_fmac_f32_e32 v4, v42, v42
	v_fmac_f32_e32 v5, v40, v40
	v_add_f32_e32 v4, v4, v5
	v_add_f32_e32 v3, v3, v4
	v_mul_f32_e32 v4, v39, v39
	v_mul_f32_e32 v5, v37, v37
	v_fmac_f32_e32 v4, v38, v38
	v_fmac_f32_e32 v5, v36, v36
	v_add_f32_e32 v4, v4, v5
	v_add_f32_e32 v3, v4, v3
	v_mul_f32_e32 v4, v35, v35
	v_mul_f32_e32 v5, v33, v33
	v_fmac_f32_e32 v4, v34, v34
	v_fmac_f32_e32 v5, v32, v32
	v_add_f32_e32 v4, v4, v5
	v_add_f32_e32 v3, v4, v3
	v_mov_b32_e32 v4, v3
	s_nop 1
	v_permlane16_swap_b32_e32 v4, v3
	s_waitcnt lgkmcnt(0)
	v_add_f32_e32 v3, v3, v4
	v_mov_b32_e32 v4, v3
	s_nop 1
	v_permlane32_swap_b32_e32 v4, v3
	s_and_saveexec_b64 s[4:5], vcc
	s_cbranch_execz .LBB0_1361
	s_waitcnt lgkmcnt(0)
	v_add_f32_e32 v3, v3, v4
	ds_write_b32 v2, v3 offset:512
.LBB0_1361:
	s_or_b64 exec, exec, s[4:5]
	v_mul_f32_e32 v3, v31, v31
	s_waitcnt lgkmcnt(0)
	v_mul_f32_e32 v4, v29, v29
	v_fmac_f32_e32 v3, v30, v30
	v_fmac_f32_e32 v4, v28, v28
	v_add_f32_e32 v3, v3, v4
	v_mul_f32_e32 v4, v27, v27
	v_mul_f32_e32 v5, v25, v25
	v_fmac_f32_e32 v4, v26, v26
	v_fmac_f32_e32 v5, v24, v24
	v_add_f32_e32 v4, v4, v5
	v_add_f32_e32 v3, v3, v4
	v_mul_f32_e32 v4, v23, v23
	v_mul_f32_e32 v5, v21, v21
	v_fmac_f32_e32 v4, v22, v22
	v_fmac_f32_e32 v5, v20, v20
	v_add_f32_e32 v4, v4, v5
	v_add_f32_e32 v3, v4, v3
	v_mul_f32_e32 v4, v19, v19
	v_mul_f32_e32 v5, v17, v17
	v_fmac_f32_e32 v4, v18, v18
	v_fmac_f32_e32 v5, v16, v16
	v_add_f32_e32 v4, v4, v5
	v_add_f32_e32 v3, v4, v3
	v_mov_b32_e32 v0, v3
	s_nop 1
	v_permlane16_swap_b32_e32 v0, v3
	s_waitcnt lgkmcnt(0)
	v_add_f32_e32 v0, v3, v0
	v_mov_b32_e32 v1, v0
	s_nop 1
	v_permlane32_swap_b32_e32 v1, v0
	s_and_saveexec_b64 s[4:5], vcc
	s_cbranch_execz .LBB0_1363
	s_waitcnt lgkmcnt(0)
	v_add_f32_e32 v0, v0, v1
	ds_write_b32 v2, v0 offset:768
